# m23 + grid barrier followers poll the scope's TOPGEN word directly (locally counted expected generation) instead of waiting for their XCD leader's XGEN release
# baseline (speedup 1.0000x reference)
; #define LAS __attribute__((address_space(3)))
; DEVI void prologue_phase(const MegaArgs& a, LAS unsigned char* lds, int wave, int lane, int gw, int ngw) {
;     unsigned char* ws = a.ws;
;     LAS float* scr = (LAS float*)(lds + wave * 8448);
;     convert_stream(a, 0, (gridDim.x == 256) ? 4 : 40, gw, ngw, scr, lane);
; #pragma unroll 1
;     for (int l = 0; l < DEPTH; ++l)
;         convert_matrix(a.in[7] + (size_t)l * DM * 1024, 1024, 1024, DM, (bf16_t*)(ws + WS_W_XKV + l * SZ_XKV), 1024 / 32, 0, gw, ngw, scr, lane);
.LBB11_9:
	s_or_b64 exec, exec, s[2:3]
	v_writelane_b32 v255, 0, 13
	v_writelane_b32 v255, 0, 14
	s_lshr_b32 s2, s10, 6
	v_writelane_b32 v249, s2, 40
	s_nop 0
	v_readlane_b32 s2, v249, 37
	s_lshl_b32 s96, s2, 3
	v_readlane_b32 s4, v249, 35
	v_readlane_b32 s5, v249, 36
	s_cmp_lt_i32 s4, 1
	s_cselect_b64 s[2:3], -1, 0
	s_cmp_gt_i32 s5, 0
	s_cselect_b64 s[4:5], -1, 0
	s_and_b64 s[2:3], s[2:3], s[4:5]
	v_cndmask_b32_e64 v1, 0, 1, s[2:3]
	v_writelane_b32 v249, s2, 41
	v_cmp_ne_u32_e64 s[6:7], 1, v1
	s_andn2_b64 vcc, exec, s[2:3]
	v_writelane_b32 v249, s3, 42
	s_cbranch_vccnz .LBB11_160
	v_readlane_b32 s2, v249, 0
	s_lshl_b32 s8, s2, 3
	v_readlane_b32 s4, v249, 37
	s_cmpk_lg_i32 s4, 0x100
	v_readlane_b32 s12, v249, 17
	s_cselect_b64 s[2:3], -1, 0
	s_cmpk_eq_i32 s4, 0x100
	v_readlane_b32 s26, v249, 31
	s_cselect_b32 s40, 4, 40
	v_readlane_b32 s27, v249, 32
	s_add_u32 s41, s26, 0x16300000
	s_addc_u32 s42, s27, 0
	s_add_u32 s43, s26, 0x2a700000
	s_addc_u32 s44, s27, 0
	s_add_u32 s45, s26, 0x28f00000
	s_addc_u32 s46, s27, 0
	s_add_u32 s47, s26, 0x26f00000
	s_addc_u32 s48, s27, 0
	s_add_u32 s49, s26, 0x23f00000
	s_addc_u32 s50, s27, 0
	s_add_u32 s51, s26, 0x21300000
	s_mov_b64 s[4:5], 0
	v_and_b32_e32 v1, 63, v0
	v_readlane_b32 s38, v249, 40
	s_addc_u32 s52, s27, 0
	s_add_u32 s53, s26, 0x300000
	v_lshlrev_b32_e32 v2, 3, v1
	s_mul_i32 s4, s38, 0x2100
	v_ashrrev_i32_e32 v17, 3, v1
	v_and_b32_e32 v6, 56, v2
	s_addc_u32 s54, s27, 0
	s_add_i32 s39, s38, s8
	s_mov_b32 s5, 0
	s_add_i32 s4, s4, 0
	v_and_b32_e32 v4, 31, v1
	v_ashrrev_i32_e32 v16, 5, v1
	s_movk_i32 s8, 0x84
	v_mul_u32_u24_e32 v2, 0x84, v6
	v_lshlrev_b32_e32 v5, 2, v17
	v_mov_b32_e32 v3, 0
	v_lshl_add_u32 v7, v4, 2, s4
	v_mul_lo_u32 v12, v16, s8
	v_add3_u32 v18, s4, v2, v5
	v_add_u32_e32 v19, 8, v17
	v_add_u32_e32 v20, 16, v17
	v_add_u32_e32 v21, 24, v17
	s_movk_i32 s55, 0x7fff
	s_mov_b32 s56, 0xffff0000
	v_lshlrev_b32_e32 v2, 2, v4
	v_mov_b32_e32 v5, 0x3f317218
	v_mov_b32_e32 v13, 0x3fb8aa3b
	s_mov_b32 s8, s5
	v_readlane_b32 s13, v249, 18
	v_readlane_b32 s14, v249, 19
	v_readlane_b32 s15, v249, 20
	v_readlane_b32 s16, v249, 21
	v_readlane_b32 s17, v249, 22
	v_readlane_b32 s18, v249, 23
	v_readlane_b32 s19, v249, 24
	v_readlane_b32 s20, v249, 25
	v_readlane_b32 s21, v249, 26
	v_readlane_b32 s22, v249, 27
	v_readlane_b32 s23, v249, 28
	v_readlane_b32 s24, v249, 29
	v_readlane_b32 s25, v249, 30
	s_branch .LBB11_13

; __device__ __forceinline__ void xcd_barrier(const XcdBarrier& b) {
;     ...
;     __syncthreads();
.LBB11_214:
	s_or_b64 exec, exec, s[4:5]
	s_waitcnt lgkmcnt(0)
	s_barrier
	v_readlane_b32 s101, v255, 13
	s_nop 3
	s_add_i32 s101, s101, 1
	s_nop 0
	v_writelane_b32 v255, s101, 13

; __device__ __forceinline__ unsigned xb_ld(unsigned* p)              { return __hip_atomic_load(p, __ATOMIC_RELAXED, __HIP_MEMORY_SCOPE_AGENT); }
; #define XB_SPIN(cond, bar) do { unsigned _sp = 0; while (cond) { __builtin_amdgcn_s_sleep(1); \
;     if ((++_sp & 255u) == 0u) { if (xb_ld(&(bar)[XB_TMO])) break; if (_sp > XB_SPIN_CAP) { atomicAdd(&(bar)[XB_TMO], 1u); break; } } } } while (0)
; __device__ __forceinline__ void xcd_barrier(const XcdBarrier& b) {
;     ...
;             XB_SPIN(xb_ld(&bar[XB_XGEN(b.x)]) == gen, bar);
.LBB11_395:
	s_or_b64 exec, exec, s[6:7]
	v_cvt_f32_u32_e32 v6, v4
	s_waitcnt vmcnt(0)
	v_readfirstlane_b32 s1, v5
	v_sub_u32_e32 v5, 0, v4
	v_rcp_iflag_f32_e32 v6, v6
	v_add_u32_e32 v7, s1, v1
	v_mul_f32_e32 v6, 0x4f7ffffe, v6
	v_cvt_u32_f32_e32 v6, v6
	v_mul_lo_u32 v1, v5, v6
	v_mul_hi_u32 v1, v6, v1
	v_add_u32_e32 v1, v6, v1
	v_mul_hi_u32 v1, v7, v1
	v_mul_lo_u32 v5, v1, v4
	v_sub_u32_e32 v5, v7, v5
	v_add_u32_e32 v6, 1, v1
	v_cmp_ge_u32_e32 vcc, v5, v4
	s_nop 1
	v_cndmask_b32_e32 v1, v1, v6, vcc
	v_sub_u32_e32 v6, v5, v4
	v_cndmask_b32_e32 v5, v5, v6, vcc
	v_add_u32_e32 v6, 1, v1
	v_cmp_ge_u32_e32 vcc, v5, v4
	v_add_u32_e32 v5, 1, v7
	s_nop 0
	v_cndmask_b32_e32 v1, v1, v6, vcc
	v_mul_lo_u32 v6, v4, v1
	v_add_u32_e32 v4, v6, v4
	v_cmp_ne_u32_e32 vcc, v5, v4
	s_and_saveexec_b64 s[6:7], vcc
	s_xor_b64 s[6:7], exec, s[6:7]
	s_cbranch_execz .LBB11_409
	v_readlane_b32 s101, v255, 13
	v_readlane_b32 s8, v255, 14
	s_nop 3
	s_cmp_eq_u32 s100, 1
	s_cselect_b32 s101, s8, s101
	v_mov_b32_e32 v1, s101
	v_readlane_b32 s8, v250, 51
	v_readlane_b32 s9, v250, 52
	s_waitcnt lgkmcnt(0)
	s_nop 3
	buffer_inv sc1
	global_load_dword v2, v3, s[8:9] sc1
	s_waitcnt vmcnt(0)
	v_cmp_eq_u32_e32 vcc, v2, v1
	s_and_saveexec_b64 s[8:9], vcc
	s_cbranch_execz .LBB11_408
	s_mov_b32 s1, 1
	s_mov_b64 s[10:11], 0
	s_branch .LBB11_399

; __device__ __forceinline__ unsigned xb_ld(unsigned* p)              { return __hip_atomic_load(p, __ATOMIC_RELAXED, __HIP_MEMORY_SCOPE_AGENT); }
; #define XB_SPIN(cond, bar) do { unsigned _sp = 0; while (cond) { __builtin_amdgcn_s_sleep(1); \
;     if ((++_sp & 255u) == 0u) { if (xb_ld(&(bar)[XB_TMO])) break; if (_sp > XB_SPIN_CAP) { atomicAdd(&(bar)[XB_TMO], 1u); break; } } } } while (0)
; __device__ __forceinline__ void xcd_barrier(const XcdBarrier& b) {
;     ...
;             XB_SPIN(xb_ld(&bar[XB_XGEN(b.x)]) == gen, bar);
.LBB11_429:
	s_or_b64 exec, exec, s[4:5]
	v_cvt_f32_u32_e32 v6, v4
	s_waitcnt vmcnt(0)
	v_readfirstlane_b32 s1, v5
	v_sub_u32_e32 v5, 0, v4
	v_rcp_iflag_f32_e32 v6, v6
	v_add_u32_e32 v7, s1, v1
	v_mul_f32_e32 v6, 0x4f7ffffe, v6
	v_cvt_u32_f32_e32 v6, v6
	v_mul_lo_u32 v1, v5, v6
	v_mul_hi_u32 v1, v6, v1
	v_add_u32_e32 v1, v6, v1
	v_mul_hi_u32 v1, v7, v1
	v_mul_lo_u32 v5, v1, v4
	v_sub_u32_e32 v5, v7, v5
	v_add_u32_e32 v6, 1, v1
	v_cmp_ge_u32_e32 vcc, v5, v4
	s_nop 1
	v_cndmask_b32_e32 v1, v1, v6, vcc
	v_sub_u32_e32 v6, v5, v4
	v_cndmask_b32_e32 v5, v5, v6, vcc
	v_add_u32_e32 v6, 1, v1
	v_cmp_ge_u32_e32 vcc, v5, v4
	v_add_u32_e32 v5, 1, v7
	s_nop 0
	v_cndmask_b32_e32 v1, v1, v6, vcc
	v_mul_lo_u32 v6, v4, v1
	v_add_u32_e32 v4, v6, v4
	v_cmp_ne_u32_e32 vcc, v5, v4
	s_and_saveexec_b64 s[4:5], vcc
	s_xor_b64 s[4:5], exec, s[4:5]
	s_cbranch_execz .LBB11_604
	v_readlane_b32 s101, v255, 13
	v_readlane_b32 s8, v255, 14
	s_nop 3
	s_cmp_eq_u32 s100, 1
	s_cselect_b32 s101, s8, s101
	v_mov_b32_e32 v1, s101
	v_readlane_b32 s8, v250, 51
	v_readlane_b32 s9, v250, 52
	s_waitcnt lgkmcnt(0)
	s_nop 3
	buffer_inv sc1
	global_load_dword v2, v3, s[8:9] sc1
	s_waitcnt vmcnt(0)
	v_cmp_eq_u32_e32 vcc, v2, v1
	s_and_saveexec_b64 s[8:9], vcc
	s_cbranch_execz .LBB11_603
	s_mov_b32 s1, 1
	s_mov_b64 s[10:11], 0
	s_branch .LBB11_433

; __device__ __forceinline__ void xcd_barrier(const XcdBarrier& b) {
;     ...
;     __syncthreads();
.LBB11_446:
	s_or_b64 exec, exec, s[4:5]
	s_waitcnt lgkmcnt(0)
	s_barrier
	s_cmp_eq_u32 s100, 1
	s_cbranch_scc1 .Lcp_13992
	v_readlane_b32 s101, v255, 13
	s_nop 3
	s_add_i32 s101, s101, 1
	s_nop 0
	v_writelane_b32 v255, s101, 13
	s_branch .Lcx_13992
.Lcp_13992:
	v_readlane_b32 s101, v255, 14
	s_nop 3
	s_add_i32 s101, s101, 1
	s_nop 0
	v_writelane_b32 v255, s101, 14
.Lcx_13992:
	s_cmp_lg_u32 s100, 1
	s_cbranch_scc1 .Lsg_ffn
	v_readlane_b32 s101, v249, 0
	s_and_b32 s101, s101, 6
	s_lshl_b32 s101, s101, 8
	s_addk_i32 s101, 0x400
	v_readlane_b32 s100, v250, 49
	s_sub_u32 s100, s100, s101
	v_writelane_b32 v250, s100, 49
	s_nop 1
	v_readlane_b32 s100, v250, 50
	s_subb_u32 s100, s100, 0
	v_writelane_b32 v250, s100, 50
	s_nop 1
	v_readlane_b32 s100, v250, 51
	s_sub_u32 s100, s100, s101
	v_writelane_b32 v250, s100, 51
	s_nop 1
	v_readlane_b32 s100, v250, 52
	s_subb_u32 s100, s100, 0
	v_writelane_b32 v250, s100, 52
	s_nop 1
	v_readlane_b32 s100, v252, 11
	s_nop 3
	v_mov_b32_e32 v1, s100
	v_readlane_b32 s100, v255, 12
	s_nop 3
	v_mov_b32_e32 v2, s100
	ds_write_b32 v1, v2
	s_waitcnt lgkmcnt(0)
	s_mov_b32 s100, 4

; __device__ __forceinline__ void xcd_barrier(const XcdBarrier& b) {
;     ...
;     __syncthreads();
.LBB11_624:
	s_or_b64 exec, exec, s[2:3]
	s_waitcnt lgkmcnt(0)
	s_barrier
	s_cmp_eq_u32 s100, 1
	s_cbranch_scc1 .Lcp_16500
	v_readlane_b32 s101, v255, 13
	s_nop 3
	s_add_i32 s101, s101, 1
	s_nop 0
	v_writelane_b32 v255, s101, 13
	s_branch .Lcx_16500

; #define STEP_BEGIN(idx, flag) if (lo <= (idx) && (idx) < hi) { for (int rep_ = 0; rep_ < (((REPEAT_MASK) & (flag)) ? 2 : 1); ++rep_) { if (prev) xcd_barrier(bar); prev = true; int lane = lane_k, wave = wave_k; size_t wz_ = 0; asm volatile("" : "+v"(lane), "+s"(wave), "+s"(wz_)); unsigned char* ws = ws_k + wz_;     const int gw = blockIdx.x * 8 + wave; (void)gw; (void)lane;
; __global__ void __launch_bounds__(512, 2) k_mega(MegaArgs a) {
;     ...
;             STEP_BEGIN(base + 1, F_XATT) { fa::cross_phase(lds, XQ, KVX, XO, l); } STEP_END
.Lcx_19282:
	s_cmp_eq_u32 s100, 4
	s_cbranch_scc1 .Ldo_xatt
	s_branch .Lsp_xatt

; __device__ __forceinline__ unsigned xb_ld(unsigned* p)              { return __hip_atomic_load(p, __ATOMIC_RELAXED, __HIP_MEMORY_SCOPE_AGENT); }
; #define XB_SPIN(cond, bar) do { unsigned _sp = 0; while (cond) { __builtin_amdgcn_s_sleep(1); \
;     if ((++_sp & 255u) == 0u) { if (xb_ld(&(bar)[XB_TMO])) break; if (_sp > XB_SPIN_CAP) { atomicAdd(&(bar)[XB_TMO], 1u); break; } } } } while (0)
; __device__ __forceinline__ void xcd_barrier(const XcdBarrier& b) {
;     ...
;             XB_SPIN(xb_ld(&bar[XB_XGEN(b.x)]) == gen, bar);
.LBB11_869:
	s_or_b64 exec, exec, s[4:5]
	v_cvt_f32_u32_e32 v6, v4
	s_waitcnt vmcnt(0)
	v_readfirstlane_b32 s1, v5
	v_sub_u32_e32 v5, 0, v4
	v_rcp_iflag_f32_e32 v6, v6
	v_add_u32_e32 v7, s1, v1
	v_mul_f32_e32 v6, 0x4f7ffffe, v6
	v_cvt_u32_f32_e32 v6, v6
	v_mul_lo_u32 v1, v5, v6
	v_mul_hi_u32 v1, v6, v1
	v_add_u32_e32 v1, v6, v1
	v_mul_hi_u32 v1, v7, v1
	v_mul_lo_u32 v5, v1, v4
	v_sub_u32_e32 v5, v7, v5
	v_add_u32_e32 v6, 1, v1
	v_cmp_ge_u32_e32 vcc, v5, v4
	s_nop 1
	v_cndmask_b32_e32 v1, v1, v6, vcc
	v_sub_u32_e32 v6, v5, v4
	v_cndmask_b32_e32 v5, v5, v6, vcc
	v_add_u32_e32 v6, 1, v1
	v_cmp_ge_u32_e32 vcc, v5, v4
	v_add_u32_e32 v5, 1, v7
	s_nop 0
	v_cndmask_b32_e32 v1, v1, v6, vcc
	v_mul_lo_u32 v6, v4, v1
	v_add_u32_e32 v4, v6, v4
	v_cmp_ne_u32_e32 vcc, v5, v4
	s_and_saveexec_b64 s[4:5], vcc
	s_xor_b64 s[4:5], exec, s[4:5]
	s_cbranch_execz .LBB11_883
	v_readlane_b32 s101, v255, 13
	v_readlane_b32 s6, v255, 14
	s_nop 3
	s_cmp_eq_u32 s100, 1
	s_cselect_b32 s101, s6, s101
	v_mov_b32_e32 v1, s101
	v_readlane_b32 s6, v250, 51
	v_readlane_b32 s7, v250, 52
	s_waitcnt lgkmcnt(0)
	s_nop 3
	buffer_inv sc1
	global_load_dword v2, v3, s[6:7] sc1
	s_waitcnt vmcnt(0)
	v_cmp_eq_u32_e32 vcc, v2, v1
	s_and_saveexec_b64 s[6:7], vcc
	s_cbranch_execz .LBB11_882
	s_mov_b32 s1, 1
	s_mov_b64 s[8:9], 0
	s_branch .LBB11_873

; #define PG8_STAGE(bufoff, gbase, voff) do { _Pragma("unroll") for (int _i = 0; _i < 2; ++_i) \
;         __builtin_amdgcn_global_load_lds((const unsigned*)((const char*)(gbase) + (voff)[_i]), (PG8_LAS unsigned*)(lds + (bufoff) + ldsw + _i * 8192), 16, 0, 0); } while (0)
; #define PG8_WAIT_V(n) asm volatile("s_waitcnt vmcnt(" #n ")" ::: "memory")
; #define PG8_BAR __builtin_amdgcn_s_barrier()
; template <class Epi, class Sched, bool ALIGN_EPI = false, bool SP2 = false>
; __device__ __forceinline__ void gemm_phase(PG8_LAS unsigned char* lds, const Gemm g, const Sched& S, const Epi& E) {
;     ...
;     const int tid = tid_, wid = __builtin_amdgcn_readfirstlane(tid >> 6), lane = tid & 63, wr = wid >> 2, wc = wid & 3, fr = lane & 15, fq = lane >> 4;
;     const int K = g.K, nt = K / BK;
;     unsigned voffA[2], voffB[2];
; #pragma unroll
;     for (int i = 0; i < 2; ++i) { int R, C; stage_rc(tid * 16 + i * 8192, R, C); const int Rb = Epi::PERM ? ((R & ~31) + perm32(R & 31)) : R;
;         voffA[i] = (unsigned)(R * K + C) * 2u; voffB[i] = (unsigned)(Rb * K + C) * 2u; }
;     const size_t kstep = (size_t)(BK * 2);
;     const size_t hstep = (size_t)HALF * K * 2;
;     const size_t tstep = 2 * hstep;
;     const unsigned ldsw = (unsigned)wid * 1024u;
;     const int aoff = lds_byte(wr * 64 + fr, fq * 8), boff = lds_byte(wc * 32 + fr, fq * 8);
;     ...
;     Unit cur, nxt; int ui = 0;
;     if (!S.next(0, cur)) return;
;     f32x4 acc[2][2][4][2];
; #pragma unroll
;     for (int a = 0; a < 2; ++a)
; #pragma unroll
;         for (int b = 0; b < 2; ++b)
; #pragma unroll
;             for (int m = 0; m < 4; ++m)
; #pragma unroll
;                 for (int n = 0; n < 2; ++n) acc[a][b][m][n] = (f32x4){0.f, 0.f, 0.f, 0.f};
;     bf16x8 At[4][2], B0[2][2], B1[2][2];
;     const char* cA = (const char*)g.A + (size_t)cur.pm * tstep; const char* cB = (const char*)g.Bt + (size_t)cur.pn * tstep;
;     S.a_ready(cur);
;     if constexpr (SP2) {
;         PG8_STAGE(PG8_SB(0, 0), cB, voffB); PG8_STAGE(PG8_SB(0, 1), cB + hstep, voffB); PG8_STAGE(PG8_SA(0, 0), cA, voffA); PG8_STAGE(PG8_SA(0, 1), cA + hstep, voffA);
;         if (wr == 1) PG8_BAR;
;         PG8_WAIT_V(2); PG8_BAR;
.Lcx_21564:
.LBB11_904:
	v_readlane_b32 s4, v251, 14
	v_readlane_b32 s1, v249, 40
	v_and_b32_e32 v1, 63, v0
	s_mov_b64 s[2:3], 0
	v_mov_b32_e32 v14, v0
	v_readlane_b32 s5, v251, 15
	s_andn2_b64 vcc, exec, s[4:5]
	v_readfirstlane_b32 s4, v14
	s_cbranch_vccnz .LBB11_920
	v_lshlrev_b32_e32 v1, 4, v14
	v_add_u32_e32 v2, 0x2000, v1
	v_ashrrev_i32_e32 v8, 31, v2
	v_lshrrev_b32_e32 v8, 22, v8
	v_add_u32_e32 v8, v2, v8
	v_ashrrev_i32_e32 v15, 10, v8
	v_mul_i32_i24_e32 v8, 0x400, v15
	v_sub_u32_e32 v2, v2, v8
	v_lshrrev_b32_e32 v8, 4, v2
	v_bitop3_b32 v2, v8, v2, 32 bitop3:0x6c
	v_ashrrev_i32_e32 v8, 31, v2
	s_mov_b32 s47, s18
	s_mul_i32 s30, s18, 0x1800000
	v_readlane_b32 s8, v249, 17
	v_lshrrev_b32_e32 v8, 26, v8
	v_mov_b64_e32 v[4:5], s[2:3]
	v_readlane_b32 s22, v249, 31
	v_readlane_b32 s23, v249, 32
	v_add_u32_e32 v8, v2, v8
	v_lshlrev_b32_e32 v9, 3, v15
	v_lshl_add_u64 v[4:5], s[22:23], 0, v[4:5]
	s_mov_b64 s[2:3], 0x47a00000
	v_ashrrev_i32_e32 v16, 6, v8
	v_and_b32_e32 v9, -16, v9
	v_lshl_add_u64 v[10:11], v[4:5], 0, s[2:3]
	v_lshl_add_u64 v[6:7], v[4:5], 0, s[30:31]
	s_mov_b64 s[2:3], 0x23f00000
	v_add_u32_e32 v9, v16, v9
	v_lshl_add_u64 v[6:7], v[6:7], 0, s[2:3]
	v_and_b32_e32 v12, 3, v16
	s_mov_b32 s2, 0xfffe0
	v_lshrrev_b32_e32 v13, 2, v9
	v_lshlrev_b32_e32 v17, 1, v9
	v_and_b32_e32 v8, 0xc0, v8
	v_and_or_b32 v12, v9, s2, v12
	v_and_b32_e32 v13, 4, v13
	v_and_b32_e32 v17, 24, v17
	v_sub_u32_e32 v2, v2, v8
	v_or3_b32 v12, v12, v13, v17
	v_lshlrev_b32_e32 v13, 5, v15
	v_ashrrev_i16_sdwa v2, v209, sext(v2) dst_sel:DWORD dst_unused:UNUSED_PAD src0_sel:DWORD src1_sel:BYTE_0
	v_and_b32_e32 v13, 32, v13
	v_bfe_i32 v17, v2, 0, 16
	v_add_lshl_u32 v2, v13, v17, 1
	s_waitcnt vmcnt(0)
	v_lshl_add_u32 v132, v12, 12, v2
	v_lshl_add_u32 v134, v9, 12, v2
	v_bfe_i32 v2, v14, 27, 1
	v_lshrrev_b32_e32 v2, 22, v2
	v_add_u32_e32 v2, v1, v2
	v_and_b32_e32 v2, 0xfffffc00, v2
	v_sub_u32_e32 v1, v1, v2
	v_lshrrev_b32_e32 v2, 4, v1
	v_ashrrev_i32_e32 v8, 31, v14
	v_bitop3_b32 v1, v2, v1, 32 bitop3:0x6c
	v_lshrrev_b32_e32 v8, 26, v8
	v_ashrrev_i32_e32 v2, 31, v1
	v_add_u32_e32 v8, v14, v8
	v_lshrrev_b32_e32 v2, 26, v2
	v_ashrrev_i32_e32 v19, 6, v8
	v_add_u32_e32 v2, v1, v2
	v_lshlrev_b32_e32 v8, 3, v19
	v_ashrrev_i32_e32 v18, 6, v2
	v_and_b32_e32 v8, -16, v8
	v_add_u32_e32 v8, v18, v8
	v_and_b32_e32 v9, 3, v18
	v_lshrrev_b32_e32 v12, 2, v8
	v_lshlrev_b32_e32 v13, 1, v8
	v_and_b32_e32 v2, 0xc0, v2
	v_and_or_b32 v9, v8, s2, v9
	v_and_b32_e32 v12, 4, v12
	v_and_b32_e32 v13, 24, v13
	v_sub_u32_e32 v1, v1, v2
	v_or3_b32 v9, v9, v12, v13
	v_lshlrev_b32_e32 v12, 5, v19
	v_ashrrev_i16_sdwa v1, v209, sext(v1) dst_sel:DWORD dst_unused:UNUSED_PAD src0_sel:DWORD src1_sel:BYTE_0
	s_ashr_i32 s6, s4, 6
	v_and_b32_e32 v12, 32, v12
	v_bfe_i32 v20, v1, 0, 16
	v_readlane_b32 s2, v251, 52
	s_lshl_b32 s23, s6, 10
	v_add_lshl_u32 v1, v12, v20, 1
	v_readlane_b32 s3, v251, 53
	v_readlane_b32 s9, v249, 18
	v_readlane_b32 s21, v249, 30
	v_lshl_add_u32 v2, v9, 12, v1
	v_lshl_add_u64 v[12:13], v[6:7], 0, s[2:3]
	s_add_i32 s24, s23, 0
	v_readlane_b32 s16, v249, 25
	v_readlane_b32 s17, v249, 26
	v_readfirstlane_b32 s21, v6
	v_readfirstlane_b32 s22, v7
	s_add_i32 m0, s24, 0x10000
	v_lshl_add_u64 v[6:7], v[12:13], 0, v[2:3]
	v_mov_b32_e32 v133, v3
	s_mov_b64 s[8:9], 0x80000
	v_lshl_add_u32 v136, v8, 12, v1
	v_readfirstlane_b32 s16, v12
	v_readfirstlane_b32 s17, v13
	global_load_lds_dwordx4 v[6:7], off
	v_lshl_add_u64 v[8:9], v[12:13], 0, v[132:133]
	s_add_i32 m0, s24, 0x12000
	v_lshl_add_u64 v[12:13], v[12:13], 0, s[8:9]
	v_readlane_b32 s2, v252, 4
	global_load_lds_dwordx4 v[8:9], off
	s_add_i32 m0, s24, 0x14000
	v_lshl_add_u64 v[22:23], v[12:13], 0, v[2:3]
	v_readlane_b32 s3, v252, 5
	v_readlane_b32 s20, v249, 29
	global_load_lds_dwordx4 v[22:23], off
	v_lshl_add_u64 v[12:13], v[12:13], 0, v[132:133]
	s_add_i32 m0, s24, 0x16000
	v_lshl_add_u64 v[22:23], v[10:11], 0, s[2:3]
	v_mov_b32_e32 v137, v3
	v_readlane_b32 s14, v249, 23
	v_readlane_b32 s15, v249, 24
	v_readfirstlane_b32 s1, v10
	v_readfirstlane_b32 s20, v11
	global_load_lds_dwordx4 v[12:13], off
	v_lshl_add_u64 v[10:11], v[22:23], 0, v[136:137]
	s_mov_b32 m0, s24
	v_mov_b32_e32 v135, v3
	s_add_i32 s25, s24, 0x2000
	v_readfirstlane_b32 s14, v22
	v_readfirstlane_b32 s15, v23
	global_load_lds_dwordx4 v[10:11], off
	v_lshl_add_u64 v[12:13], v[22:23], 0, v[134:135]
	s_mov_b32 m0, s25
	v_lshl_add_u64 v[22:23], v[22:23], 0, s[8:9]
	s_add_i32 s26, s24, 0x4000
	global_load_lds_dwordx4 v[12:13], off
	v_lshl_add_u64 v[24:25], v[22:23], 0, v[136:137]
	s_mov_b32 m0, s26
	s_add_i32 s27, s24, 0x6000
	global_load_lds_dwordx4 v[24:25], off
	v_lshl_add_u64 v[22:23], v[22:23], 0, v[134:135]
	s_mov_b32 m0, s27
	s_ashr_i32 s5, s4, 8
	global_load_lds_dwordx4 v[22:23], off
	s_cmp_eq_u32 s5, 1
	s_cselect_b64 s[2:3], -1, 0
	s_cmp_lg_u32 s5, 1
	v_readlane_b32 s10, v249, 19
	v_readlane_b32 s11, v249, 20
	v_readlane_b32 s12, v249, 21
	v_readlane_b32 s13, v249, 22
	v_readlane_b32 s18, v249, 27
	v_readlane_b32 s19, v249, 28
	s_cbranch_scc1 .LBB11_907
	s_barrier

; #define LAS __attribute__((address_space(3)))
; DEVI int otid() { int t = threadIdx.x; asm volatile("" : "+v"(t)); return t; }
; DEVI void stick_phase(LAS unsigned char* lds, const bf16_t* QKV, bf16_t* O) {
;     const int wid = otid() >> 6;
;     for (int u = blockIdx.x; u < NB * 16 * 4; u += gridDim.x) {
;         const int pq = u & 3, h = (u >> 2) & 15, b = u >> 6;
; #pragma unroll 1
;         for (int s = 0; s < 2; ++s) { const int qb = s == 0 ? 7 - pq : pq; const int tw = qb * 256 + wid * 32, m0 = b * SEQ + tw, cw = tw >> 6;
;             attn_unit<M_STICK>(lds, QKV + (size_t)m0 * ODD_COLS + h * HD, ODD_COLS, QKV + (size_t)(b * SEQ) * ODD_COLS + 2048 + h * HD, QKV + (size_t)(b * SEQ) * ODD_COLS + 4096 + h * HD, ODD_COLS,
;                                O + (size_t)m0 * DM + h * HD, DM, 4 * qb + 3, 4 * qb + 4, -1, 0, cw, tw); }
.Lcx_23243:
.LBB11_976:
	v_readlane_b32 s1, v249, 40
	s_mov_b64 s[2:3], 0
	v_and_b32_e32 v1, 63, v0
	v_readlane_b32 s4, v251, 16
	v_readlane_b32 s5, v251, 17
	v_mov_b32_e32 v1, v0
	s_andn2_b64 vcc, exec, s[4:5]
	s_cbranch_vccnz .LBB11_1004
	v_readlane_b32 s4, v249, 17
	v_mov_b64_e32 v[4:5], s[2:3]
	v_readlane_b32 s18, v249, 31
	v_readlane_b32 s19, v249, 32
	s_mov_b64 s[2:3], 0x53200000
	v_ashrrev_i32_e32 v1, 1, v1
	v_lshl_add_u64 v[116:117], s[18:19], 0, v[4:5]
	v_lshl_add_u64 v[118:119], v[116:117], 0, s[2:3]
	s_mov_b64 s[2:3], 0x59200000
	v_readlane_b32 s1, v255, 8
	v_lshl_add_u64 v[120:121], v[116:117], 0, s[2:3]
	s_waitcnt vmcnt(0)
	v_and_b32_e32 v137, 0xffffffe0, v1
	v_readlane_b32 s2, v251, 59
	s_mov_b32 s4, s1
	v_readlane_b32 s5, v249, 18
	v_readlane_b32 s6, v249, 19
	v_readlane_b32 s7, v249, 20
	v_readlane_b32 s8, v249, 21
	v_readlane_b32 s9, v249, 22
	v_readlane_b32 s10, v249, 23
	v_readlane_b32 s11, v249, 24
	v_readlane_b32 s12, v249, 25
	v_readlane_b32 s13, v249, 26
	v_readlane_b32 s14, v249, 27
	v_readlane_b32 s15, v249, 28
	v_readlane_b32 s16, v249, 29
	v_readlane_b32 s17, v249, 30
	s_branch .LBB11_979

; __device__ __forceinline__ void xcd_barrier(const XcdBarrier& b) {
;     ...
;     __syncthreads();
.LBB11_1266:
	s_or_b64 exec, exec, s[2:3]
	v_readlane_b32 s4, v249, 17
	v_readlane_b32 s18, v249, 31
	v_readlane_b32 s19, v249, 32
	s_waitcnt lgkmcnt(0)
	s_barrier
	v_readlane_b32 s5, v249, 18
	v_readlane_b32 s6, v249, 19
	v_readlane_b32 s7, v249, 20
	v_readlane_b32 s8, v249, 21
	v_readlane_b32 s9, v249, 22
	v_readlane_b32 s10, v249, 23
	v_readlane_b32 s11, v249, 24
	v_readlane_b32 s12, v249, 25
	v_readlane_b32 s13, v249, 26
	v_readlane_b32 s14, v249, 27
	v_readlane_b32 s15, v249, 28
	v_readlane_b32 s16, v249, 29
	v_readlane_b32 s17, v249, 30
	s_cmp_eq_u32 s100, 1
	s_cbranch_scc1 .Lcp_30023
	v_readlane_b32 s101, v255, 13
	s_nop 3
	s_add_i32 s101, s101, 1
	s_nop 0
	v_writelane_b32 v255, s101, 13
	s_branch .Lcx_30023

; __device__ __forceinline__ unsigned xb_ld(unsigned* p)              { return __hip_atomic_load(p, __ATOMIC_RELAXED, __HIP_MEMORY_SCOPE_AGENT); }
; #define XB_SPIN(cond, bar) do { unsigned _sp = 0; while (cond) { __builtin_amdgcn_s_sleep(1); \
;     if ((++_sp & 255u) == 0u) { if (xb_ld(&(bar)[XB_TMO])) break; if (_sp > XB_SPIN_CAP) { atomicAdd(&(bar)[XB_TMO], 1u); break; } } } } while (0)
; __device__ __forceinline__ void xcd_barrier(const XcdBarrier& b) {
;     ...
;             XB_SPIN(xb_ld(&bar[XB_XGEN(b.x)]) == gen, bar);
.LBB11_1845:
	s_or_b64 exec, exec, s[4:5]
	v_cvt_f32_u32_e32 v6, v4
	s_waitcnt vmcnt(0)
	v_readfirstlane_b32 s1, v5
	v_sub_u32_e32 v5, 0, v4
	v_rcp_iflag_f32_e32 v6, v6
	v_add_u32_e32 v7, s1, v1
	v_mul_f32_e32 v6, 0x4f7ffffe, v6
	v_cvt_u32_f32_e32 v6, v6
	v_mul_lo_u32 v1, v5, v6
	v_mul_hi_u32 v1, v6, v1
	v_add_u32_e32 v1, v6, v1
	v_mul_hi_u32 v1, v7, v1
	v_mul_lo_u32 v5, v1, v4
	v_sub_u32_e32 v5, v7, v5
	v_add_u32_e32 v6, 1, v1
	v_cmp_ge_u32_e32 vcc, v5, v4
	s_nop 1
	v_cndmask_b32_e32 v1, v1, v6, vcc
	v_sub_u32_e32 v6, v5, v4
	v_cndmask_b32_e32 v5, v5, v6, vcc
	v_add_u32_e32 v6, 1, v1
	v_cmp_ge_u32_e32 vcc, v5, v4
	v_add_u32_e32 v5, 1, v7
	s_nop 0
	v_cndmask_b32_e32 v1, v1, v6, vcc
	v_mul_lo_u32 v6, v4, v1
	v_add_u32_e32 v4, v6, v4
	v_cmp_ne_u32_e32 vcc, v5, v4
	s_and_saveexec_b64 s[4:5], vcc
	s_xor_b64 s[4:5], exec, s[4:5]
	s_cbranch_execz .LBB11_1859
	v_readlane_b32 s101, v255, 13
	v_readlane_b32 s14, v255, 14
	s_nop 3
	s_cmp_eq_u32 s100, 1
	s_cselect_b32 s101, s14, s101
	v_mov_b32_e32 v1, s101
	v_readlane_b32 s14, v250, 51
	v_readlane_b32 s15, v250, 52
	s_waitcnt lgkmcnt(0)
	s_nop 3
	buffer_inv sc1
	global_load_dword v2, v3, s[14:15] sc1
	s_waitcnt vmcnt(0)
	v_cmp_eq_u32_e32 vcc, v2, v1
	s_and_saveexec_b64 s[14:15], vcc
	s_cbranch_execz .LBB11_1858
	s_mov_b32 s1, 1
	s_mov_b64 s[16:17], 0
	s_branch .LBB11_1849

; #define STEP_BEGIN(idx, flag) if (lo <= (idx) && (idx) < hi) { for (int rep_ = 0; rep_ < (((REPEAT_MASK) & (flag)) ? 2 : 1); ++rep_) { if (prev) xcd_barrier(bar); prev = true; int lane = lane_k, wave = wave_k; size_t wz_ = 0; asm volatile("" : "+v"(lane), "+s"(wave), "+s"(wz_)); unsigned char* ws = ws_k + wz_;     const int gw = blockIdx.x * 8 + wave; (void)gw; (void)lane;
; __global__ void __launch_bounds__(512, 2) k_mega(MegaArgs a) {
;     ...
;             STEP_BEGIN(base + 5, F_OUT) {
;                 unsigned* ctl = (unsigned*)(ws + WS_CTL);
;     ...
;                 pg8::EpiLnFused E{(sb == 0) ? a.in[0] : (const float*)nullptr, XB, (sb == 15) ? a.out : nullptr, DM, lng, lnb, ALPHA, ocs, st};
;                 run_gemm_fused(lds, oA, oB, MT, DM, oK, E);
.Lcx_40373:
	s_cmp_eq_u32 s100, 4
	s_cbranch_scc1 .Ldo_out
	s_cmp_lg_u32 s100, 0
	s_cbranch_scc1 .Lsp_out
	v_readlane_b32 s100, v249, 31
	v_readlane_b32 s101, v249, 32
	s_add_u32 s100, s100, 0x8000
	s_addc_u32 s101, s101, 0
	v_mbcnt_lo_u32_b32 v1, -1, 0
	v_mbcnt_hi_u32_b32 v1, -1, v1
	v_lshlrev_b32_e32 v1, 2, v1
	global_load_dword v2, v1, s[100:101] sc1
	s_waitcnt vmcnt(0)
	v_bcnt_u32_b32 v1, v2, 0
	v_cmp_lt_u32_e32 vcc, 1, v1
	s_nop 1
	v_readlane_b32 s100, v252, 11
	s_nop 3
	v_mov_b32_e32 v1, s100
	ds_read_b32 v2, v1
	s_waitcnt lgkmcnt(0)
	v_readfirstlane_b32 s100, v2
	s_nop 3
	v_writelane_b32 v255, s100, 12
	s_barrier
	s_cmp_lg_u64 vcc, 0
	s_mov_b32 s100, 2
	s_cbranch_scc1 .Lsp_out
